# attention loop: K-base xors and loop-carried move hoisted ahead of the step barrier; back edge is a single conditional branch
# speedup vs baseline: 1.0061x; 1.0061x over previous
; __device__ __forceinline__ void finishSM(f32x16& p0, f32x16& p1, float alpha, float& l_reg, bf16x8& pa0, bf16x8& pa1, bf16x8& pa2, bf16x8& pa3) {
;     for (int r = 0; r < 16; ++r) p1[r] = __builtin_amdgcn_exp2f(p1[r]);
;     float ps = 0; for (int r = 0; r < 16; ++r) ps += p0[r]; for (int r = 0; r < 16; ++r) ps += p1[r];
;     { auto rr = __builtin_amdgcn_permlane32_swap(__float_as_uint(ps), __float_as_uint(ps), false, false);
;       ps = __uint_as_float(rr[0]) + __uint_as_float(rr[1]); }
;     l_reg = l_reg * alpha + ps;
;     ...
;     PK4(p0, 0, pa0); PK4(p0, 8, pa1); PK4(p1, 0, pa2); PK4(p1, 8, pa3);
;     ...
; }
; template <int KB>
; __device__ __forceinline__ void qkt(f32x16& p0, f32x16& p1, const char* K_lds, int r32, int hi, const bf16x8* qr) {
;     p0 = f32x16{}; p1 = f32x16{};
;     const char* kb[4];
; #pragma unroll
;     for (int dd = 0; dd < 4; ++dd) kb[dd] = K_lds + KB * SHM_K + KSWZ(r32, (dd * 16 + hi * 8) * 2);
; #pragma unroll
;     for (int d0 = 0; d0 < 8; ++d0) { const char* a = kb[d0 & 3] + (d0 >> 2) * 128;
;         bf16x8 b0 = *reinterpret_cast<const bf16x8*>(a);
;         bf16x8 b1 = *reinterpret_cast<const bf16x8*>(a + 32 * 256);
;         p0 = __builtin_amdgcn_mfma_f32_32x32x16_bf16(b0, qr[d0], p0, 0, 0, 0);
;         p1 = __builtin_amdgcn_mfma_f32_32x32x16_bf16(b1, qr[d0], p1, 0, 0, 0); }
; }
; template <int VB>
; __device__ __forceinline__ void pv_tile(f32x16* o, int vb0, bf16x8 pa0, bf16x8 pa1, bf16x8 pa2, bf16x8 pa3) {
;     ...
;     PV_D0(0); PV_D0(1); PV_D0(2); PV_D0(3);
.LBB0_320:
	ds_read_b128 v[64:67], v201 offset:49152
	ds_read_b128 v[68:71], v201 offset:57344
	ds_read_b128 v[96:99], v230 offset:49152
	ds_read_b128 v[100:103], v230 offset:57344
	v_exp_f32_e32 v104, v126
	v_exp_f32_e32 v105, v127
	s_waitcnt lgkmcnt(3)
	v_mfma_f32_32x32x16_bf16 v[80:95], v[64:67], v[156:159], 0
	v_exp_f32_e32 v106, v122
	v_exp_f32_e32 v107, v123
	v_exp_f32_e32 v108, v118
	v_exp_f32_e32 v109, v119
	v_exp_f32_e32 v110, v116
	v_exp_f32_e32 v111, v117
	v_exp_f32_e32 v112, v112
	s_waitcnt lgkmcnt(2)
	v_mfma_f32_32x32x16_bf16 v[64:79], v[68:71], v[156:159], 0
	v_exp_f32_e32 v113, v113
	v_exp_f32_e32 v116, v124
	v_exp_f32_e32 v117, v125
	v_exp_f32_e32 v118, v120
	v_exp_f32_e32 v119, v121
	v_exp_f32_e32 v114, v114
	v_exp_f32_e32 v115, v115
	s_waitcnt lgkmcnt(1)
	v_mfma_f32_32x32x16_bf16 v[80:95], v[96:99], v[152:155], v[80:95]
	s_waitcnt lgkmcnt(0)
	v_mfma_f32_32x32x16_bf16 v[64:79], v[100:103], v[152:155], v[64:79]
	ds_read_b128 v[96:99], v229 offset:49152
	ds_read_b128 v[100:103], v229 offset:57344
	s_waitcnt lgkmcnt(1)
	v_mfma_f32_32x32x16_bf16 v[80:95], v[96:99], v[148:151], v[80:95]
	s_waitcnt lgkmcnt(0)
	v_mfma_f32_32x32x16_bf16 v[64:79], v[100:103], v[148:151], v[64:79]
	ds_read_b128 v[96:99], v207 offset:49152
	ds_read_b128 v[100:103], v207 offset:57344
	s_waitcnt lgkmcnt(1)
	v_mfma_f32_32x32x16_bf16 v[80:95], v[96:99], v[144:147], v[80:95]
	s_waitcnt lgkmcnt(0)
	v_mfma_f32_32x32x16_bf16 v[64:79], v[100:103], v[144:147], v[64:79]
	ds_read_b128 v[96:99], v250 offset:49152
	ds_read_b128 v[100:103], v250 offset:57344
	s_waitcnt lgkmcnt(1)
	v_mfma_f32_32x32x16_bf16 v[80:95], v[96:99], v[140:143], v[80:95]
	s_waitcnt lgkmcnt(0)
	v_mfma_f32_32x32x16_bf16 v[64:79], v[100:103], v[140:143], v[64:79]
	ds_read_b128 v[96:99], v251 offset:49152
	ds_read_b128 v[100:103], v251 offset:57344
	s_waitcnt lgkmcnt(1)
	v_mfma_f32_32x32x16_bf16 v[80:95], v[96:99], v[136:139], v[80:95]
	s_waitcnt lgkmcnt(0)
	v_mfma_f32_32x32x16_bf16 v[64:79], v[100:103], v[136:139], v[64:79]
	ds_read_b128 v[96:99], v252 offset:49152
	ds_read_b128 v[100:103], v252 offset:57344
	s_waitcnt lgkmcnt(1)
	v_mfma_f32_32x32x16_bf16 v[80:95], v[96:99], v[132:135], v[80:95]
	s_waitcnt lgkmcnt(0)
	v_mfma_f32_32x32x16_bf16 v[64:79], v[100:103], v[132:135], v[64:79]
	ds_read_b128 v[96:99], v253 offset:49152
	ds_read_b128 v[100:103], v253 offset:57344
	ds_read_b64_tr_b16 v[238:239], v225 offset:0
	ds_read_b64_tr_b16 v[240:241], v225 offset:0x800
	ds_read_b64_tr_b16 v[242:243], v225 offset:0x1000
	ds_read_b64_tr_b16 v[244:245], v225 offset:0x1800
	ds_read_b64_tr_b16 v[246:247], v225 offset:0x2000
	ds_read_b64_tr_b16 v[248:249], v225 offset:0x2800
	ds_read_b64_tr_b16 v[250:251], v225 offset:0x3000
	ds_read_b64_tr_b16 v[252:253], v225 offset:0x3800
	s_waitcnt lgkmcnt(9)
	v_mfma_f32_32x32x16_bf16 v[80:95], v[96:99], v[128:131], v[80:95]
	v_add_f32_e32 v96, 0, v169
	v_add_f32_e32 v96, v170, v96
	v_add_f32_e32 v96, v171, v96
	v_add_f32_e32 v96, v173, v96
	v_add_f32_e32 v96, v174, v96
	v_add_f32_e32 v96, v177, v96
	v_add_f32_e32 v96, v172, v96
	v_add_f32_e32 v96, v175, v96
	v_add_f32_e32 v96, v161, v96
	v_add_f32_e32 v96, v163, v96
	v_add_f32_e32 v96, v164, v96
	v_add_f32_e32 v96, v167, v96
	v_add_f32_e32 v96, v162, v96
	v_add_f32_e32 v96, v165, v96
	v_add_f32_e32 v96, v166, v96
	v_add_f32_e32 v96, v168, v96
	v_add_f32_e32 v96, v104, v96
	v_add_f32_e32 v96, v105, v96
	v_add_f32_e32 v96, v106, v96
	v_add_f32_e32 v96, v107, v96
	v_add_f32_e32 v96, v108, v96
	v_add_f32_e32 v96, v109, v96
	v_add_f32_e32 v96, v110, v96
	v_add_f32_e32 v96, v111, v96
	v_add_f32_e32 v96, v112, v96
	v_add_f32_e32 v96, v113, v96
	s_waitcnt lgkmcnt(8)
; __device__ __forceinline__ void finishSM(f32x16& p0, f32x16& p1, float alpha, float& l_reg, bf16x8& pa0, bf16x8& pa1, bf16x8& pa2, bf16x8& pa3) {
;     ...
;     float ps = 0; for (int r = 0; r < 16; ++r) ps += p0[r]; for (int r = 0; r < 16; ++r) ps += p1[r];
;     { auto rr = __builtin_amdgcn_permlane32_swap(__float_as_uint(ps), __float_as_uint(ps), false, false);
;       ps = __uint_as_float(rr[0]) + __uint_as_float(rr[1]); }
;     l_reg = l_reg * alpha + ps;
;     ...
;     PK4(p0, 0, pa0); PK4(p0, 8, pa1); PK4(p1, 0, pa2); PK4(p1, 8, pa3);
;     ...
; }
; template <int KB>
; __device__ __forceinline__ void qkt(f32x16& p0, f32x16& p1, const char* K_lds, int r32, int hi, const bf16x8* qr) {
;     p0 = f32x16{}; p1 = f32x16{};
;     const char* kb[4];
; #pragma unroll
;     for (int dd = 0; dd < 4; ++dd) kb[dd] = K_lds + KB * SHM_K + KSWZ(r32, (dd * 16 + hi * 8) * 2);
; #pragma unroll
;     for (int d0 = 0; d0 < 8; ++d0) { const char* a = kb[d0 & 3] + (d0 >> 2) * 128;
;         bf16x8 b0 = *reinterpret_cast<const bf16x8*>(a);
;         bf16x8 b1 = *reinterpret_cast<const bf16x8*>(a + 32 * 256);
;         p0 = __builtin_amdgcn_mfma_f32_32x32x16_bf16(b0, qr[d0], p0, 0, 0, 0);
;         p1 = __builtin_amdgcn_mfma_f32_32x32x16_bf16(b1, qr[d0], p1, 0, 0, 0); }
; }
; template <int VB>
; __device__ __forceinline__ void pv_tile(f32x16* o, int vb0, bf16x8 pa0, bf16x8 pa1, bf16x8 pa2, bf16x8 pa3) {
;     ...
;     PV_D0(0); PV_D0(1); PV_D0(2); PV_D0(3);
	v_mfma_f32_32x32x16_bf16 v[64:79], v[100:103], v[128:131], v[64:79]
	v_add_f32_e32 v96, v116, v96
	v_add_f32_e32 v96, v117, v96
	v_add_f32_e32 v96, v118, v96
	v_add_f32_e32 v96, v119, v96
	v_add_f32_e32 v96, v114, v96
	v_add_f32_e32 v194, v115, v96
	v_mov_b32_e32 v234, v194
	v_cvt_pk_bf16_f32 v96, v169, v170
	v_cvt_pk_bf16_f32 v97, v171, v173
	v_cvt_pk_bf16_f32 v98, v174, v177
	v_cvt_pk_bf16_f32 v99, v172, v175
	v_permlane32_swap_b32_e32 v194, v234
	v_permlane32_swap_b32_e32 v96, v98
	v_permlane32_swap_b32_e32 v97, v99
	v_cvt_pk_bf16_f32 v100, v161, v163
	v_cvt_pk_bf16_f32 v101, v164, v167
	v_cvt_pk_bf16_f32 v102, v162, v165
	v_cvt_pk_bf16_f32 v103, v166, v168
	v_cvt_pk_bf16_f32 v104, v104, v105
	v_cvt_pk_bf16_f32 v105, v106, v107
	v_cvt_pk_bf16_f32 v106, v108, v109
	v_cvt_pk_bf16_f32 v107, v110, v111
	v_cvt_pk_bf16_f32 v108, v112, v113
	v_cvt_pk_bf16_f32 v109, v116, v117
	v_cvt_pk_bf16_f32 v110, v118, v119
	v_cvt_pk_bf16_f32 v111, v114, v115
	v_permlane32_swap_b32_e32 v100, v102
	v_permlane32_swap_b32_e32 v101, v103
	v_permlane32_swap_b32_e32 v104, v106
	v_permlane32_swap_b32_e32 v105, v107
	v_permlane32_swap_b32_e32 v108, v110
	v_permlane32_swap_b32_e32 v109, v111
	v_add_u32_e32 v212, s50, v202
	v_ashrrev_i32_e32 v213, 31, v212
	v_add_u32_e32 v116, 32, v212
	v_lshlrev_b64 v[112:113], 8, v[212:213]
	v_ashrrev_i32_e32 v117, 31, v116
	v_lshl_add_u64 v[114:115], v[208:209], 0, v[112:113]
	v_lshlrev_b64 v[116:117], 8, v[116:117]
	v_lshl_add_u64 v[112:113], v[210:211], 0, v[112:113]
	v_lshl_add_u64 v[118:119], v[208:209], 0, v[116:117]
	global_load_dwordx4 v[160:163], v[114:115], off
	global_load_dwordx4 v[164:167], v[118:119], off
	v_lshl_add_u64 v[114:115], v[210:211], 0, v[116:117]
	global_load_dwordx4 v[168:171], v[112:113], off
	global_load_dwordx4 v[172:175], v[114:115], off
	s_waitcnt lgkmcnt(0)
	s_nop 0
	v_mfma_f32_32x32x16_bf16 v[0:15], v[96:99], v[238:241], v[0:15]
	ds_read_b64_tr_b16 v[112:113], v225 offset:0x200
	ds_read_b64_tr_b16 v[114:115], v225 offset:0xa00
	v_mfma_f32_32x32x16_bf16 v[0:15], v[100:103], v[242:245], v[0:15]
	ds_read_b64_tr_b16 v[116:117], v225 offset:0x1200
	ds_read_b64_tr_b16 v[118:119], v225 offset:0x1a00
	v_mfma_f32_32x32x16_bf16 v[0:15], v[104:107], v[246:249], v[0:15]
	ds_read_b64_tr_b16 v[120:121], v225 offset:0x2200
	ds_read_b64_tr_b16 v[122:123], v225 offset:0x2a00
	v_mfma_f32_32x32x16_bf16 v[0:15], v[108:111], v[250:253], v[0:15]
	ds_read_b64_tr_b16 v[124:125], v225 offset:0x3200
	ds_read_b64_tr_b16 v[126:127], v225 offset:0x3a00
	s_waitcnt lgkmcnt(0)
	v_mfma_f32_32x32x16_bf16 v[48:63], v[96:99], v[112:115], v[48:63]
	ds_read_b64_tr_b16 v[112:113], v225 offset:0x400
	ds_read_b64_tr_b16 v[114:115], v225 offset:0xc00
	v_mfma_f32_32x32x16_bf16 v[48:63], v[100:103], v[116:119], v[48:63]
	ds_read_b64_tr_b16 v[116:117], v225 offset:0x1400
	ds_read_b64_tr_b16 v[118:119], v225 offset:0x1c00
	v_mfma_f32_32x32x16_bf16 v[48:63], v[104:107], v[120:123], v[48:63]
	ds_read_b64_tr_b16 v[120:121], v225 offset:0x2400
	ds_read_b64_tr_b16 v[122:123], v225 offset:0x2c00
	v_mfma_f32_32x32x16_bf16 v[48:63], v[108:111], v[124:127], v[48:63]
	ds_read_b64_tr_b16 v[124:125], v225 offset:0x3400
	ds_read_b64_tr_b16 v[126:127], v225 offset:0x3c00
	s_waitcnt lgkmcnt(0)
	v_mfma_f32_32x32x16_bf16 v[32:47], v[96:99], v[112:115], v[32:47]
	ds_read_b64_tr_b16 v[112:113], v225 offset:0x600
	ds_read_b64_tr_b16 v[114:115], v225 offset:0xe00
	v_mfma_f32_32x32x16_bf16 v[32:47], v[100:103], v[116:119], v[32:47]
	ds_read_b64_tr_b16 v[116:117], v225 offset:0x1600
	ds_read_b64_tr_b16 v[118:119], v225 offset:0x1e00
	v_mfma_f32_32x32x16_bf16 v[32:47], v[104:107], v[120:123], v[32:47]
	ds_read_b64_tr_b16 v[120:121], v225 offset:0x2600
	ds_read_b64_tr_b16 v[122:123], v225 offset:0x2e00
	v_mfma_f32_32x32x16_bf16 v[32:47], v[108:111], v[124:127], v[32:47]
	ds_read_b64_tr_b16 v[124:125], v225 offset:0x3600
	ds_read_b64_tr_b16 v[126:127], v225 offset:0x3e00
	s_waitcnt lgkmcnt(0)
	s_waitcnt vmcnt(0)
	ds_write_b128 v231, v[160:163] offset:16384
	ds_write_b128 v232, v[164:167] offset:16384
	ds_write_b128 v226, v[168:171] offset:32768
	ds_write_b128 v226, v[172:175] offset:40960
	s_sub_i32 s40, s50, 64
	s_cmp_gt_i32 s40, s49
	s_cbranch_scc0 .Lmy_nomask1
	v_mov_b32_e32 v64, v220
	v_mov_b32_e32 v65, v220
	v_mov_b32_e32 v66, v220
	v_mov_b32_e32 v67, v220
	v_mov_b32_e32 v68, v220
	v_mov_b32_e32 v69, v220
	v_mov_b32_e32 v70, v220
	v_mov_b32_e32 v71, v220
	v_mov_b32_e32 v72, v220
	v_mov_b32_e32 v73, v220
	v_mov_b32_e32 v74, v220
	v_mov_b32_e32 v75, v220
	v_mov_b32_e32 v76, v220
	v_mov_b32_e32 v77, v220
	v_mov_b32_e32 v78, v220
	v_mov_b32_e32 v79, v220
	v_mov_b32_e32 v80, v220
	v_mov_b32_e32 v81, v220
	v_mov_b32_e32 v82, v220
	v_mov_b32_e32 v83, v220
	v_mov_b32_e32 v84, v220
	v_mov_b32_e32 v85, v220
	v_mov_b32_e32 v86, v220
	v_mov_b32_e32 v87, v220
	v_mov_b32_e32 v88, v220
	v_mov_b32_e32 v89, v220
	v_mov_b32_e32 v90, v220
	v_mov_b32_e32 v91, v220
	v_mov_b32_e32 v92, v220
	v_mov_b32_e32 v93, v220
	v_mov_b32_e32 v94, v220
	v_mov_b32_e32 v95, v220

; __device__ __forceinline__ void partialSM(f32x16& p0, f32x16& p1, float& m_reg, float& mn, float& alpha) {
;     float pmax = p0[0]; for (int r = 1; r < 16; ++r) pmax = fmaxf(pmax, p0[r]); for (int r = 0; r < 16; ++r) pmax = fmaxf(pmax, p1[r]);
;     { auto rr = __builtin_amdgcn_permlane32_swap(__float_as_uint(pmax), __float_as_uint(pmax), false, false);
;       pmax = fmaxf(__uint_as_float(rr[0]), __uint_as_float(rr[1])); }
;     constexpr float C2 = 1.4426950408889634f * SCALE;
;     if (__builtin_expect(__all((pmax - m_reg) * SCALE <= THR), 1)) { mn = m_reg; alpha = 1.f; }
;     else { mn = fmaxf(m_reg, pmax); alpha = __builtin_amdgcn_exp2f((m_reg - mn) * C2); m_reg = mn; }
;     const float mnL = -mn * C2;
;     for (int r = 0; r < 16; ++r) p0[r] = fmaf(p0[r], C2, mnL); for (int r = 0; r < 16; ++r) p1[r] = fmaf(p1[r], C2, mnL);
;     for (int r = 0; r < 16; ++r) p0[r] = __builtin_amdgcn_exp2f(p0[r]);
.LBB0_324:
	v_cndmask_b32_e64 v235, v77, v176, s[40:41]
	v_mul_f32_e32 v176, 0xbe0293ee, v235
	v_fmamk_f32 v77, v98, 0x3e0293ee, v176
	v_fmamk_f32 v78, v97, 0x3e0293ee, v176
	v_fmamk_f32 v79, v96, 0x3e0293ee, v176
	v_fmamk_f32 v96, v83, 0x3e0293ee, v176
	v_fmamk_f32 v97, v84, 0x3e0293ee, v176
	v_fmamk_f32 v98, v85, 0x3e0293ee, v176
	v_fmamk_f32 v99, v86, 0x3e0293ee, v176
	v_fmamk_f32 v100, v87, 0x3e0293ee, v176
	v_fmamk_f32 v101, v88, 0x3e0293ee, v176
	v_fmamk_f32 v102, v89, 0x3e0293ee, v176
	v_fmamk_f32 v103, v90, 0x3e0293ee, v176
	v_fmamk_f32 v104, v91, 0x3e0293ee, v176
	v_fmamk_f32 v105, v92, 0x3e0293ee, v176
	v_fmamk_f32 v106, v93, 0x3e0293ee, v176
	v_fmamk_f32 v107, v94, 0x3e0293ee, v176
	v_fmamk_f32 v108, v95, 0x3e0293ee, v176
	v_fmamk_f32 v83, v64, 0x3e0293ee, v176
	v_fmamk_f32 v84, v65, 0x3e0293ee, v176
	v_fmamk_f32 v93, v66, 0x3e0293ee, v176
	v_fmamk_f32 v94, v67, 0x3e0293ee, v176
	v_fmamk_f32 v95, v68, 0x3e0293ee, v176
	v_fmamk_f32 v85, v69, 0x3e0293ee, v176
	v_fmamk_f32 v86, v70, 0x3e0293ee, v176
	v_fmamk_f32 v87, v71, 0x3e0293ee, v176
	v_fmamk_f32 v88, v72, 0x3e0293ee, v176
	v_fmamk_f32 v89, v73, 0x3e0293ee, v176
	v_fmamk_f32 v90, v74, 0x3e0293ee, v176
	v_fmamk_f32 v91, v75, 0x3e0293ee, v176
	v_fmamk_f32 v92, v76, 0x3e0293ee, v176
	v_exp_f32_e32 v64, v77
	v_exp_f32_e32 v65, v78
	v_exp_f32_e32 v66, v79
	v_exp_f32_e32 v67, v96
	v_exp_f32_e32 v68, v97
	v_exp_f32_e32 v69, v98
	v_exp_f32_e32 v70, v99
	v_exp_f32_e32 v71, v100
	v_exp_f32_e32 v72, v101
	v_exp_f32_e32 v73, v102
	v_exp_f32_e32 v74, v103
	v_exp_f32_e32 v75, v104
	v_exp_f32_e32 v76, v105
	v_exp_f32_e32 v77, v106
	v_exp_f32_e32 v78, v107
	v_exp_f32_e32 v79, v108
	v_fmamk_f32 v177, v82, 0x3e0293ee, v176
	v_fmamk_f32 v178, v81, 0x3e0293ee, v176
	v_fmac_f32_e32 v176, 0x3e0293ee, v80
	v_xor_b32_e32 v250, 0x80, v201
	v_xor_b32_e32 v251, 0x80, v230
	v_xor_b32_e32 v252, 0x80, v229
	v_xor_b32_e32 v253, 0x80, v207
	s_waitcnt lgkmcnt(0)
	s_barrier
; __device__ __forceinline__ void finishSM(f32x16& p0, f32x16& p1, float alpha, float& l_reg, bf16x8& pa0, bf16x8& pa1, bf16x8& pa2, bf16x8& pa3) {
;     for (int r = 0; r < 16; ++r) p1[r] = __builtin_amdgcn_exp2f(p1[r]);
;     float ps = 0; for (int r = 0; r < 16; ++r) ps += p0[r]; for (int r = 0; r < 16; ++r) ps += p1[r];
;     { auto rr = __builtin_amdgcn_permlane32_swap(__float_as_uint(ps), __float_as_uint(ps), false, false);
;       ps = __uint_as_float(rr[0]) + __uint_as_float(rr[1]); }
;     l_reg = l_reg * alpha + ps;
;     ...
;     PK4(p0, 0, pa0); PK4(p0, 8, pa1); PK4(p1, 0, pa2); PK4(p1, 8, pa3);
;     ...
; }
; template <int KB>
; __device__ __forceinline__ void qkt(f32x16& p0, f32x16& p1, const char* K_lds, int r32, int hi, const bf16x8* qr) {
;     p0 = f32x16{}; p1 = f32x16{};
;     const char* kb[4];
; #pragma unroll
;     for (int dd = 0; dd < 4; ++dd) kb[dd] = K_lds + KB * SHM_K + KSWZ(r32, (dd * 16 + hi * 8) * 2);
; #pragma unroll
;     for (int d0 = 0; d0 < 8; ++d0) { const char* a = kb[d0 & 3] + (d0 >> 2) * 128;
;         bf16x8 b0 = *reinterpret_cast<const bf16x8*>(a);
;         bf16x8 b1 = *reinterpret_cast<const bf16x8*>(a + 32 * 256);
;         p0 = __builtin_amdgcn_mfma_f32_32x32x16_bf16(b0, qr[d0], p0, 0, 0, 0);
;         p1 = __builtin_amdgcn_mfma_f32_32x32x16_bf16(b1, qr[d0], p1, 0, 0, 0); }
; }
; template <int VB>
; __device__ __forceinline__ void pv_tile(f32x16* o, int vb0, bf16x8 pa0, bf16x8 pa1, bf16x8 pa2, bf16x8 pa3) {
;     ...
;     PV_D0(0); PV_D0(1); PV_D0(2); PV_D0(3);
	ds_read_b128 v[96:99], v201 offset:32768
	ds_read_b128 v[100:103], v201 offset:40960
	ds_read_b128 v[180:183], v230 offset:32768
	ds_read_b128 v[184:187], v230 offset:40960
	v_exp_f32_e32 v81, v84
	v_exp_f32_e32 v84, v95
	s_waitcnt lgkmcnt(3)
	v_mfma_f32_32x32x16_bf16 v[112:127], v[96:99], v[156:159], 0
	v_exp_f32_e32 v95, v176
	v_add_f32_e32 v176, 0, v64
	v_add_f32_e32 v176, v65, v176
	v_add_f32_e32 v176, v66, v176
	v_add_f32_e32 v176, v67, v176
	v_add_f32_e32 v176, v68, v176
	v_add_f32_e32 v176, v69, v176
	s_waitcnt lgkmcnt(2)
	v_mfma_f32_32x32x16_bf16 v[96:111], v[100:103], v[156:159], 0
	v_add_f32_e32 v176, v70, v176
	v_add_f32_e32 v176, v71, v176
	v_add_f32_e32 v176, v72, v176
	v_add_f32_e32 v176, v73, v176
	v_add_f32_e32 v176, v74, v176
	v_add_f32_e32 v176, v75, v176
	v_exp_f32_e32 v80, v83
	s_waitcnt lgkmcnt(1)
	v_mfma_f32_32x32x16_bf16 v[112:127], v[180:183], v[152:155], v[112:127]
	v_add_f32_e32 v176, v76, v176
	v_add_f32_e32 v176, v77, v176
	v_exp_f32_e32 v82, v93
	v_add_f32_e32 v176, v78, v176
	v_exp_f32_e32 v83, v94
	v_add_f32_e32 v176, v79, v176
	v_add_f32_e32 v176, v80, v176
	s_waitcnt lgkmcnt(0)
	v_mfma_f32_32x32x16_bf16 v[96:111], v[184:187], v[152:155], v[96:111]
	ds_read_b128 v[180:183], v229 offset:32768
	ds_read_b128 v[184:187], v229 offset:40960
	v_exp_f32_e32 v85, v85
	v_add_f32_e32 v176, v81, v176
	v_exp_f32_e32 v86, v86
	v_add_f32_e32 v176, v82, v176
	v_exp_f32_e32 v87, v87
	v_add_f32_e32 v176, v83, v176
	s_waitcnt lgkmcnt(1)
	v_mfma_f32_32x32x16_bf16 v[112:127], v[180:183], v[148:151], v[112:127]
	v_exp_f32_e32 v88, v88
	v_add_f32_e32 v176, v84, v176
	v_exp_f32_e32 v89, v89
	v_add_f32_e32 v176, v85, v176
	v_exp_f32_e32 v90, v90
	v_add_f32_e32 v176, v86, v176
	v_exp_f32_e32 v91, v91
	s_waitcnt lgkmcnt(0)
	v_mfma_f32_32x32x16_bf16 v[96:111], v[184:187], v[148:151], v[96:111]
	ds_read_b128 v[180:183], v207 offset:32768
	ds_read_b128 v[184:187], v207 offset:40960
	v_add_f32_e32 v176, v87, v176
	v_exp_f32_e32 v92, v92
	v_add_f32_e32 v176, v88, v176
	v_exp_f32_e32 v93, v177
	v_add_f32_e32 v176, v89, v176
	v_exp_f32_e32 v94, v178
	s_waitcnt lgkmcnt(1)
	v_mfma_f32_32x32x16_bf16 v[112:127], v[180:183], v[144:147], v[112:127]
	v_add_f32_e32 v176, v90, v176
	v_add_f32_e32 v176, v91, v176
	v_add_f32_e32 v176, v92, v176
	v_add_f32_e32 v176, v93, v176
	v_add_f32_e32 v176, v94, v176
	v_add_f32_e32 v236, v95, v176
	v_mov_b32_e32 v237, v236
	s_waitcnt lgkmcnt(0)
	v_mfma_f32_32x32x16_bf16 v[96:111], v[184:187], v[144:147], v[96:111]
	ds_read_b128 v[180:183], v250 offset:32768
	ds_read_b128 v[184:187], v250 offset:40960
	v_cvt_pk_bf16_f32 v176, v64, v65
	v_cvt_pk_bf16_f32 v177, v66, v67
	v_cvt_pk_bf16_f32 v178, v68, v69
	v_cvt_pk_bf16_f32 v179, v70, v71
	v_cvt_pk_bf16_f32 v188, v88, v89
	v_cvt_pk_bf16_f32 v189, v90, v91
	s_waitcnt lgkmcnt(1)
	v_mfma_f32_32x32x16_bf16 v[112:127], v[180:183], v[140:143], v[112:127]
	v_cvt_pk_bf16_f32 v190, v92, v93
	v_cvt_pk_bf16_f32 v191, v94, v95
	v_permlane32_swap_b32_e32 v236, v237
	v_permlane32_swap_b32_e32 v176, v178
	v_permlane32_swap_b32_e32 v177, v179
	s_waitcnt lgkmcnt(0)
	v_mfma_f32_32x32x16_bf16 v[96:111], v[184:187], v[140:143], v[96:111]
	ds_read_b128 v[180:183], v251 offset:32768
	ds_read_b128 v[184:187], v251 offset:40960
	v_permlane32_swap_b32_e32 v188, v190
	v_permlane32_swap_b32_e32 v189, v191
	s_waitcnt lgkmcnt(1)
	v_mfma_f32_32x32x16_bf16 v[112:127], v[180:183], v[136:139], v[112:127]
	s_waitcnt lgkmcnt(0)
	v_mfma_f32_32x32x16_bf16 v[96:111], v[184:187], v[136:139], v[96:111]
	ds_read_b128 v[180:183], v252 offset:32768
	ds_read_b128 v[184:187], v252 offset:40960
	s_waitcnt lgkmcnt(1)
	v_mfma_f32_32x32x16_bf16 v[112:127], v[180:183], v[132:135], v[112:127]
	s_waitcnt lgkmcnt(0)
	v_mfma_f32_32x32x16_bf16 v[96:111], v[184:187], v[132:135], v[96:111]
	ds_read_b128 v[180:183], v253 offset:32768
	ds_read_b128 v[184:187], v253 offset:40960
	ds_read_b64_tr_b16 v[238:239], v225 offset:0x4000
	ds_read_b64_tr_b16 v[240:241], v225 offset:0x4800
	ds_read_b64_tr_b16 v[242:243], v225 offset:0x5000
	ds_read_b64_tr_b16 v[244:245], v225 offset:0x5800
	ds_read_b64_tr_b16 v[246:247], v225 offset:0x6000
	ds_read_b64_tr_b16 v[248:249], v225 offset:0x6800
	ds_read_b64_tr_b16 v[250:251], v225 offset:0x7000
	ds_read_b64_tr_b16 v[252:253], v225 offset:0x7800
	s_waitcnt lgkmcnt(9)
	v_mfma_f32_32x32x16_bf16 v[112:127], v[180:183], v[128:131], v[112:127]
	v_cvt_pk_bf16_f32 v180, v72, v73
	v_cvt_pk_bf16_f32 v181, v74, v75
	v_cvt_pk_bf16_f32 v182, v76, v77
	v_cvt_pk_bf16_f32 v183, v78, v79
	s_nop 0
	v_permlane32_swap_b32_e32 v180, v182
	v_permlane32_swap_b32_e32 v181, v183
	s_waitcnt lgkmcnt(8)
	v_mfma_f32_32x32x16_bf16 v[96:111], v[184:187], v[128:131], v[96:111]
	v_cvt_pk_bf16_f32 v184, v80, v81
	v_cvt_pk_bf16_f32 v185, v82, v83
	v_cvt_pk_bf16_f32 v186, v84, v85
	v_cvt_pk_bf16_f32 v187, v86, v87
	s_nop 0
	v_permlane32_swap_b32_e32 v184, v186
	v_permlane32_swap_b32_e32 v185, v187
	s_add_i32 s40, s80, 1
	s_cmp_lt_u32 s40, s79
	s_cselect_b64 s[42:43], -1, 0
	s_cmp_ge_u32 s40, s79
	s_cbranch_scc1 .LBB0_326
	v_add_u32_e32 v160, 64, v212
	v_add_u32_e32 v162, 0x60, v212
	v_ashrrev_i32_e32 v161, 31, v160
	v_ashrrev_i32_e32 v163, 31, v162
	v_lshlrev_b64 v[168:169], 8, v[160:161]
	v_lshlrev_b64 v[170:171], 8, v[162:163]
	v_lshl_add_u64 v[160:161], v[208:209], 0, v[168:169]
	v_lshl_add_u64 v[164:165], v[208:209], 0, v[170:171]
	v_lshl_add_u64 v[168:169], v[210:211], 0, v[168:169]
	v_lshl_add_u64 v[172:173], v[210:211], 0, v[170:171]
	global_load_dwordx4 v[160:163], v[160:161], off
	s_nop 0
	global_load_dwordx4 v[164:167], v[164:165], off
	s_nop 0
	global_load_dwordx4 v[168:171], v[168:169], off
	s_nop 0
	global_load_dwordx4 v[172:175], v[172:173], off

; __device__ __forceinline__ void partialSM(f32x16& p0, f32x16& p1, float& m_reg, float& mn, float& alpha) {
;     ...
;     constexpr float C2 = 1.4426950408889634f * SCALE;
;     if (__builtin_expect(__all((pmax - m_reg) * SCALE <= THR), 1)) { mn = m_reg; alpha = 1.f; }
;     else { mn = fmaxf(m_reg, pmax); alpha = __builtin_amdgcn_exp2f((m_reg - mn) * C2); m_reg = mn; }
;     const float mnL = -mn * C2;
;     for (int r = 0; r < 16; ++r) p0[r] = fmaf(p0[r], C2, mnL); for (int r = 0; r < 16; ++r) p1[r] = fmaf(p1[r], C2, mnL);
;     for (int r = 0; r < 16; ++r) p0[r] = __builtin_amdgcn_exp2f(p0[r]);
; }
; __device__ __forceinline__ void finishSM(f32x16& p0, f32x16& p1, float alpha, float& l_reg, bf16x8& pa0, bf16x8& pa1, bf16x8& pa2, bf16x8& pa3) {
;     for (int r = 0; r < 16; ++r) p1[r] = __builtin_amdgcn_exp2f(p1[r]);
;     float ps = 0; for (int r = 0; r < 16; ++r) ps += p0[r]; for (int r = 0; r < 16; ++r) ps += p1[r];
;     { auto rr = __builtin_amdgcn_permlane32_swap(__float_as_uint(ps), __float_as_uint(ps), false, false);
;       ps = __uint_as_float(rr[0]) + __uint_as_float(rr[1]); }
;     l_reg = l_reg * alpha + ps;
; __device__ __forceinline__ void attn_block(const BlockRef& cur, const BlockRef& nxt, char* lds, Seam& S) {
;     ...
;     for (int t = 1; t + 1 < NT; t += 2) {
;         HALF_STEP(pB0, pB1, mnB, alB, pA0, pA1, alA, t, 1, 0, 0);
;         HALF_STEP(pA0, pA1, mnA, alA, pB0, pB1, alB, t + 1, 0, 1, 1);
;     }
.LBB0_332:
	v_cndmask_b32_e64 v176, v161, v235, s[40:41]
	v_mul_f32_e32 v178, 0xbe0293ee, v176
	v_mov_b32_e32 v180, v178
	v_fmamk_f32 v161, v112, 0x3e0293ee, v178
	v_fmamk_f32 v162, v113, 0x3e0293ee, v178
	v_fmamk_f32 v114, v114, 0x3e0293ee, v178
	v_fmamk_f32 v115, v115, 0x3e0293ee, v178
	v_fmamk_f32 v163, v116, 0x3e0293ee, v178
	s_waitcnt vmcnt(2)
	v_fmamk_f32 v164, v117, 0x3e0293ee, v178
	v_fmamk_f32 v165, v118, 0x3e0293ee, v178
	v_fmamk_f32 v166, v119, 0x3e0293ee, v178
	v_fmamk_f32 v120, v120, 0x3e0293ee, v178
	v_fmamk_f32 v121, v121, 0x3e0293ee, v178
	v_fmamk_f32 v167, v122, 0x3e0293ee, v178
	s_waitcnt vmcnt(1)
	v_fmamk_f32 v168, v123, 0x3e0293ee, v178
	v_fmamk_f32 v124, v124, 0x3e0293ee, v178
	v_fmamk_f32 v125, v125, 0x3e0293ee, v178
	v_fmamk_f32 v179, v126, 0x3e0293ee, v178
	v_fmac_f32_e32 v180, 0x3e0293ee, v127
	v_exp_f32_e32 v169, v161
	v_exp_f32_e32 v170, v162
	v_exp_f32_e32 v171, v114
	s_waitcnt vmcnt(0)
	v_exp_f32_e32 v173, v115
	v_exp_f32_e32 v174, v163
	v_exp_f32_e32 v177, v164
	v_exp_f32_e32 v172, v165
	v_exp_f32_e32 v175, v166
	v_exp_f32_e32 v161, v120
	v_exp_f32_e32 v163, v121
	v_exp_f32_e32 v164, v167
	v_exp_f32_e32 v167, v168
	v_exp_f32_e32 v162, v124
	v_exp_f32_e32 v165, v125
	v_exp_f32_e32 v166, v179
	v_exp_f32_e32 v168, v180
	v_pk_fma_f32 v[126:127], v[96:97], s[26:27], v[178:179] op_sel_hi:[1,0,0]
	v_add_f32_e32 v96, v194, v234
	v_fmac_f32_e32 v96, v233, v228
	v_add_f32_e32 v228, v236, v237
	s_addk_i32 s50, 0x80
	s_add_i32 s80, s80, 2
	v_pk_fma_f32 v[122:123], v[98:99], s[26:27], v[178:179] op_sel_hi:[1,0,0]
	v_pk_fma_f32 v[118:119], v[100:101], s[26:27], v[178:179] op_sel_hi:[1,0,0]
	v_pk_fma_f32 v[116:117], v[102:103], s[26:27], v[178:179] op_sel_hi:[1,0,0]
	v_pk_fma_f32 v[112:113], v[104:105], s[26:27], v[178:179] op_sel_hi:[1,0,0]
	v_pk_fma_f32 v[124:125], v[106:107], s[26:27], v[178:179] op_sel_hi:[1,0,0]
	v_pk_fma_f32 v[120:121], v[108:109], s[26:27], v[178:179] op_sel_hi:[1,0,0]
	v_pk_fma_f32 v[114:115], v[110:111], s[26:27], v[178:179] op_sel_hi:[1,0,0]
	v_fmac_f32_e32 v228, v96, v213
	v_xor_b32_e32 v250, 0x80, v201
	v_xor_b32_e32 v251, 0x80, v230
	v_xor_b32_e32 v252, 0x80, v229
	v_xor_b32_e32 v253, 0x80, v207
	v_mov_b32_e32 v233, v160
	s_cmp_ge_u32 s80, s79
	s_waitcnt lgkmcnt(0)
	s_barrier
	s_cbranch_scc0 .LBB0_320

; #define PG8_WAIT_V(n) asm volatile("s_waitcnt vmcnt(" #n ")" ::: "memory")
; #define PG8_BAR __builtin_amdgcn_s_barrier()
; template <class Epi, class Sched, bool ALIGN_EPI = false, bool SP2 = false>
; __device__ __forceinline__ void gemm_phase(PG8_LAS unsigned char* lds, const Gemm g, const Sched& S, const Epi& E) {
;     ...
;     const int tid = tid_, wid = __builtin_amdgcn_readfirstlane(tid >> 6), lane = tid & 63, wr = wid >> 2, wc = wid & 3, fr = lane & 15, fq = lane >> 4;
;     const int K = g.K, nt = K / BK;
;     unsigned voffA[2], voffB[2];
; #pragma unroll
;     for (int i = 0; i < 2; ++i) { int R, C; stage_rc(tid * 16 + i * 8192, R, C); const int Rb = Epi::PERM ? ((R & ~31) + perm32(R & 31)) : R;
;         voffA[i] = (unsigned)(R * K + C) * 2u; voffB[i] = (unsigned)(Rb * K + C) * 2u; }
;     const size_t kstep = (size_t)(BK * 2);
;     const size_t hstep = (size_t)HALF * K * 2;
;     const size_t tstep = 2 * hstep;
;     const unsigned ldsw = (unsigned)wid * 1024u;
;     const int aoff = lds_byte(wr * 64 + fr, fq * 8), boff = lds_byte(wc * 32 + fr, fq * 8);
;     ...
;     Unit cur, nxt; int ui = 0;
;     if (!S.next(0, cur)) return;
;     f32x4 acc[2][2][4][2];
; #pragma unroll
;     for (int a = 0; a < 2; ++a)
; #pragma unroll
;         for (int b = 0; b < 2; ++b)
; #pragma unroll
;             for (int m = 0; m < 4; ++m)
; #pragma unroll
;                 for (int n = 0; n < 2; ++n) acc[a][b][m][n] = (f32x4){0.f, 0.f, 0.f, 0.f};
;     bf16x8 At[4][2], B0[2][2], B1[2][2];
;     const char* cA = (const char*)g.A + (size_t)cur.pm * tstep; const char* cB = (const char*)g.Bt + (size_t)cur.pn * tstep;
;     S.a_ready(cur);
;     if constexpr (SP2) {
;         PG8_STAGE(PG8_SB(0, 0), cB, voffB); PG8_STAGE(PG8_SB(0, 1), cB + hstep, voffB); PG8_STAGE(PG8_SA(0, 0), cA, voffA); PG8_STAGE(PG8_SA(0, 1), cA + hstep, voffA);
;         if (wr == 1) PG8_BAR;
;         PG8_WAIT_V(2); PG8_BAR;
;         PG8_STAGE(PG8_SB(1, 0), cB + kstep, voffB); PG8_STAGE(PG8_SA(1, 0), cA + kstep, voffA); PG8_STAGE(PG8_SB(1, 1), cB + hstep + kstep, voffB);
;         PG8_WAIT_V(6); PG8_BAR;
;     } else {
;         PG8_STAGE(PG8_SB(0, 0), cB, voffB); PG8_STAGE(PG8_SA(0, 0), cA, voffA); PG8_STAGE(PG8_SB(0, 1), cB + hstep, voffB); PG8_STAGE(PG8_SA(0, 1), cA + hstep, voffA);
;         if (wr == 1) PG8_BAR;
.LBB0_540:
	s_or_b64 exec, exec, s[14:15]
	s_nop 0
	s_nop 0
	s_nop 0
	s_nop 0
	s_nop 0
	s_nop 0
	s_nop 0
	s_nop 0
	s_nop 0
	s_nop 0
	s_nop 0
	s_nop 0
	s_nop 0
	s_cmpk_lt_i32 s2, 0x400
	s_mov_b64 s[22:23], s[0:1]
	s_mov_b64 s[16:17], s[0:1]
	s_mov_b64 s[24:25], s[0:1]
	s_mov_b64 s[18:19], s[0:1]
	s_mov_b64 s[14:15], s[0:1]
	s_waitcnt lgkmcnt(0)
	s_barrier
	s_cselect_b64 s[48:49], -1, 0
	s_lshr_b32 s13, s33, 29
	s_add_i32 s13, s2, s13
	s_load_dwordx2 s[14:15], s[14:15], 0xc8
	s_ashr_i32 s56, s13, 3
	s_and_b32 s13, s13, -8
	s_load_dwordx2 s[20:21], s[16:17], 0xc8
	s_nop 0
	s_load_dwordx2 s[18:19], s[18:19], 0xc8
	s_mov_b64 s[16:17], s[0:1]
	s_sub_i32 s59, s2, s13
	s_cmp_lt_i32 s59, 0
	s_load_dwordx2 s[16:17], s[16:17], 0xc8
	s_cselect_b64 s[42:43], -1, 0
	s_lshl_b32 s57, s59, 7
	s_waitcnt lgkmcnt(0)
	s_add_u32 s14, s14, 0x2f800000
	s_addc_u32 s15, s15, 0
	s_waitcnt vmcnt(27)
	v_mov_b32_e32 v14, v216
	s_cmpk_gt_i32 s2, 0x3ff
	s_mul_i32 s58, s59, 0x81
	s_nop 0
	v_readfirstlane_b32 s28, v14
	s_cbranch_scc1 .LBB0_560
	v_lshlrev_b32_e32 v0, 4, v14
	v_add_u32_e32 v1, 0x2000, v0
	v_ashrrev_i32_e32 v2, 31, v1
	v_lshrrev_b32_e32 v2, 22, v2
	v_add_u32_e32 v2, v1, v2
	v_ashrrev_i32_e32 v8, 10, v2
	v_mul_i32_i24_e32 v2, 0x400, v8
	v_sub_u32_e32 v1, v1, v2
	v_lshrrev_b32_e32 v2, 4, v1
	v_bitop3_b32 v1, v2, v1, 32 bitop3:0x6c
	v_ashrrev_i32_e32 v2, 31, v1
	s_load_dwordx2 s[22:23], s[22:23], 0xc8
	s_nop 0
	s_load_dwordx2 s[24:25], s[24:25], 0xc8
	v_lshrrev_b32_e32 v2, 26, v2
	v_add_u32_e32 v2, v1, v2
	v_lshlrev_b32_e32 v3, 3, v8
	v_ashrrev_i32_e32 v9, 6, v2
	v_and_b32_e32 v3, -16, v3
	v_add_u32_e32 v3, v9, v3
	s_waitcnt lgkmcnt(0)
	s_add_u32 s13, s22, 0x3b800000
	v_and_b32_e32 v4, 3, v9
	s_mov_b32 s22, 0x1fffe0
	v_lshrrev_b32_e32 v5, 2, v3
	v_lshlrev_b32_e32 v6, 1, v3
	v_and_b32_e32 v2, 0xc0, v2
	v_and_or_b32 v4, v3, s22, v4
	v_and_b32_e32 v5, 4, v5
	v_and_b32_e32 v6, 24, v6
	v_sub_u32_e32 v1, v1, v2
	v_mov_b32_e32 v2, 1
	v_or3_b32 v4, v4, v5, v6
	v_lshlrev_b32_e32 v5, 5, v8
	v_ashrrev_i16_sdwa v1, v2, sext(v1) dst_sel:DWORD dst_unused:UNUSED_PAD src0_sel:DWORD src1_sel:BYTE_0
	v_and_b32_e32 v5, 32, v5
	v_bfe_i32 v10, v1, 0, 16
	v_add_lshl_u32 v1, v5, v10, 1
	s_waitcnt vmcnt(6)
	v_lshl_add_u32 v152, v4, 11, v1
	v_lshl_add_u32 v154, v3, 11, v1
	v_bfe_i32 v1, v14, 27, 1
	v_lshrrev_b32_e32 v1, 22, v1
	v_add_u32_e32 v1, v0, v1
	v_and_b32_e32 v1, 0xfffffc00, v1
	v_sub_u32_e32 v0, v0, v1
	v_lshrrev_b32_e32 v1, 4, v0
	v_ashrrev_i32_e32 v3, 31, v14
	v_bitop3_b32 v0, v1, v0, 32 bitop3:0x6c
	v_lshrrev_b32_e32 v3, 26, v3
	v_ashrrev_i32_e32 v1, 31, v0
	v_add_u32_e32 v3, v14, v3
	s_addc_u32 s47, s23, 0
	v_lshrrev_b32_e32 v1, 26, v1
	v_ashrrev_i32_e32 v12, 6, v3
	s_add_u32 s60, s24, 0x2600000
	v_add_u32_e32 v1, v0, v1
	v_lshlrev_b32_e32 v3, 3, v12
	s_addc_u32 s61, s25, 0
	s_ashr_i32 s26, s28, 6
	v_ashrrev_i32_e32 v11, 6, v1
	v_and_b32_e32 v3, -16, v3
	s_ashr_i32 s27, s28, 8
	s_lshl_b32 s62, s26, 10
	v_add_u32_e32 v3, v11, v3
	v_and_b32_e32 v4, 3, v11
	v_and_or_b32 v4, v3, s22, v4
	s_and_b64 s[22:23], s[42:43], exec
	s_cselect_b32 s22, s58, s57
	s_add_i32 s22, s22, s56
	s_ashr_i32 s23, s22, 31
	s_lshr_b32 s23, s23, 27
	s_add_i32 s23, s22, s23
	s_ashr_i32 s24, s23, 5
	s_and_b32 s23, s23, 0xffe0
	s_sub_i32 s22, s22, s23
	s_bfe_i32 s23, s22, 0x80000
	s_bfe_u32 s23, s23, 0x2000d
	s_add_i32 s23, s22, s23
	s_lshl_b32 s25, s24, 2
	s_bfe_i32 s24, s23, 0x80000
	s_and_b32 s23, s23, 0xfc
	s_sub_i32 s22, s22, s23
	s_sext_i32_i16 s24, s24
	s_sext_i32_i8 s22, s22
	v_lshrrev_b32_e32 v5, 2, v3
	v_lshlrev_b32_e32 v6, 1, v3
	v_and_b32_e32 v1, 0xc0, v1
	s_lshr_b32 s24, s24, 2
	s_add_i32 s44, s25, s22
	v_and_b32_e32 v5, 4, v5
	v_and_b32_e32 v6, 24, v6
	v_sub_u32_e32 v0, v0, v1
	s_ashr_i32 s45, s44, 31
	s_bfe_i64 s[30:31], s[24:25], 0x100000
	v_or3_b32 v4, v4, v5, v6
	v_lshlrev_b32_e32 v5, 5, v12
	v_ashrrev_i16_sdwa v0, v2, sext(v0) dst_sel:DWORD dst_unused:UNUSED_PAD src0_sel:DWORD src1_sel:BYTE_0
	s_lshl_b64 s[22:23], s[44:45], 19
	s_lshl_b64 s[30:31], s[30:31], 19
	v_and_b32_e32 v5, 32, v5
	v_bfe_i32 v13, v0, 0, 16
	s_add_u32 s52, s60, s30
	v_add_lshl_u32 v0, v5, v13, 1
	s_addc_u32 s53, s61, s31
	s_add_i32 s63, s62, 0
	v_lshl_add_u32 v156, v4, 11, v0
	s_add_i32 m0, s63, 0x10000
	v_lshl_add_u32 v158, v3, 11, v0
	global_load_lds_dwordx4 v156, s[52:53]
	s_add_i32 m0, s63, 0x12000
	s_add_u32 s30, s52, 0x40000
	global_load_lds_dwordx4 v152, s[52:53]
	s_addc_u32 s31, s53, 0
	s_add_i32 m0, s63, 0x14000
	v_mov_b32_e32 v157, 0
	global_load_lds_dwordx4 v156, s[30:31]
	s_add_i32 m0, s63, 0x16000
	s_add_u32 s50, s13, s22
	s_addc_u32 s51, s47, s23
	s_add_i32 s64, s63, 0x2000
	global_load_lds_dwordx4 v152, s[30:31]
	s_mov_b32 m0, s63
	s_add_u32 s22, s50, 0x40000
	global_load_lds_dwordx4 v158, s[50:51]
	s_mov_b32 m0, s64
	s_addc_u32 s23, s51, 0
	s_add_i32 s65, s63, 0x4000
	global_load_lds_dwordx4 v154, s[50:51]
	s_mov_b32 m0, s65
	s_add_i32 s66, s63, 0x6000
	global_load_lds_dwordx4 v158, s[22:23]
	s_mov_b32 m0, s66
	v_mov_b32_e32 v153, v157
	global_load_lds_dwordx4 v154, s[22:23]
	v_mov_b32_e32 v159, v157
	v_mov_b32_e32 v155, v157
	s_cmp_eq_u32 s27, 1
	v_lshl_add_u64 v[6:7], s[52:53], 0, v[156:157]
	v_lshl_add_u64 v[4:5], s[52:53], 0, v[152:153]
	v_lshl_add_u64 v[0:1], s[50:51], 0, v[158:159]
	s_cselect_b64 s[22:23], -1, 0
	s_cmp_lg_u32 s27, 1
	v_lshl_add_u64 v[2:3], s[50:51], 0, v[154:155]
	s_cbranch_scc1 .LBB0_543
	s_barrier
